# M13 + P8 epilogue: rstd loads issued before waiting for the column-scale loads (one fewer L2 round trip per tile)
# speedup vs baseline: 1.0060x; 1.0060x over previous
.LBB0_1109:
	v_lshl_or_b32 v170, s74, 7, v209
	v_ashrrev_i32_e32 v171, 31, v170
	v_lshl_add_u64 v[106:107], v[170:171], 2, s[12:13]
	global_load_dwordx4 v[140:143], v[106:107], off offset:16
	s_mov_b64 s[54:55], 0x5800
	global_load_dwordx4 v[142:145], v[106:107], off
	v_lshl_add_u64 v[108:109], v[106:107], 0, s[54:55]
	v_add_co_u32_e32 v106, vcc, 0x5000, v106
	s_mov_b64 s[54:55], 0
	s_nop 0
	v_addc_co_u32_e32 v107, vcc, 0, v107, vcc
	global_load_dwordx4 v[136:139], v[106:107], off offset:2048
	s_nop 0
	global_load_dwordx4 v[106:109], v[108:109], off offset:16
	v_lshl_add_u32 v250, s76, 8, v207
	v_ashrrev_i32_e32 v251, 31, v250
	v_lshl_add_u64 v[248:249], v[250:251], 2, s[6:7]
	global_load_dword v198, v[248:249], off
	global_load_dword v194, v[248:249], off offset:64
	global_load_dword v192, v[248:249], off offset:128
	global_load_dword v196, v[248:249], off offset:192
	v_add_u32_e32 v248, 0x80, v250
	v_ashrrev_i32_e32 v249, 31, v248
	v_lshl_add_u64 v[248:249], v[248:249], 2, s[6:7]
	global_load_dword v178, v[248:249], off
	v_add_u32_e32 v248, 0x90, v250
	v_ashrrev_i32_e32 v249, 31, v248
	v_lshl_add_u64 v[248:249], v[248:249], 2, s[6:7]
	global_load_dword v174, v[248:249], off
	v_add_u32_e32 v248, 0xa0, v250
	v_add_u32_e32 v250, 0xb0, v250
	v_ashrrev_i32_e32 v249, 31, v248
	v_ashrrev_i32_e32 v251, 31, v250
	v_lshl_add_u64 v[248:249], v[248:249], 2, s[6:7]
	v_lshl_add_u64 v[250:251], v[250:251], 2, s[6:7]
	global_load_dword v172, v[248:249], off
	global_load_dword v176, v[250:251], off
	s_waitcnt vmcnt(8)
	v_cmp_lt_i32_e32 vcc, 14, v206
	s_and_saveexec_b64 s[68:69], vcc
	s_xor_b64 s[78:79], exec, s[68:69]
	s_mov_b64 s[54:55], exec
	s_or_saveexec_b64 s[78:79], s[78:79]
	v_cvt_f32_i32_e32 v109, v133
	v_cvt_f32_i32_e32 v108, v132
	v_cvt_f32_i32_e32 v133, v135
	v_cvt_f32_i32_e32 v132, v134
	v_cvt_f32_i32_e32 v129, v129
	v_cvt_f32_i32_e32 v128, v128
	v_cvt_f32_i32_e32 v131, v131
	v_cvt_f32_i32_e32 v130, v130
	v_cvt_f32_i32_e32 v139, v103
	v_cvt_f32_i32_e32 v138, v102
	v_cvt_f32_i32_e32 v145, v105
	v_cvt_f32_i32_e32 v144, v104
	v_cvt_f32_i32_e32 v93, v93
	v_cvt_f32_i32_e32 v92, v92
	v_mul_f32_e32 v190, 0x3c010204, v142
	v_cvt_f32_i32_e32 v91, v91
	v_cvt_f32_i32_e32 v90, v90
	v_mul_f32_e32 v180, 0x3c010204, v140
	s_waitcnt vmcnt(7)
	v_mul_f32_e32 v102, v190, v198
	v_pk_mul_f32 v[134:135], v[102:103], v[132:133] op_sel_hi:[0,1]
	v_pk_mul_f32 v[132:133], v[102:103], v[108:109] op_sel_hi:[0,1]
	v_mul_f32_e32 v102, v180, v198
	s_waitcnt vmcnt(4)
	v_mul_f32_e32 v108, v190, v196
	v_pk_mul_f32 v[104:105], v[102:103], v[130:131] op_sel_hi:[0,1]
	v_pk_mul_f32 v[102:103], v[102:103], v[128:129] op_sel_hi:[0,1]
	v_pk_mul_f32 v[130:131], v[108:109], v[144:145] op_sel_hi:[0,1]
	v_pk_mul_f32 v[128:129], v[108:109], v[138:139] op_sel_hi:[0,1]
	v_mul_f32_e32 v108, v180, v196
	v_pk_mul_f32 v[92:93], v[108:109], v[92:93] op_sel_hi:[0,1]
	v_pk_mul_f32 v[90:91], v[108:109], v[90:91] op_sel_hi:[0,1]
	v_mov_b64_e32 v[140:141], v[92:93]
	v_mov_b64_e32 v[144:145], v[130:131]
	v_mov_b32_e32 v107, s89
	v_mov_b64_e32 v[138:139], v[90:91]
	v_mov_b64_e32 v[142:143], v[128:129]
	s_xor_b64 exec, exec, s[78:79]
	s_andn2_b64 s[54:55], s[54:55], exec
	s_and_b64 s[68:69], s[38:39], exec
	v_mov_b64_e32 v[140:141], v[104:105]
	v_mov_b64_e32 v[144:145], v[134:135]
	v_mov_b32_e32 v107, s88
	s_or_b64 s[54:55], s[54:55], s[68:69]
	v_mov_b64_e32 v[138:139], v[102:103]
	v_mov_b64_e32 v[142:143], v[132:133]
	s_or_b64 exec, exec, s[78:79]
	v_cvt_f32_i32_e32 v71, v71
	v_cvt_f32_i32_e32 v70, v70
	v_cvt_f32_i32_e32 v73, v73
	v_cvt_f32_i32_e32 v72, v72
	v_cvt_f32_i32_e32 v63, v63
	v_cvt_f32_i32_e32 v62, v62
	v_cvt_f32_i32_e32 v65, v65
	v_cvt_f32_i32_e32 v64, v64
	v_cvt_f32_i32_e32 v109, v43
	v_cvt_f32_i32_e32 v108, v42
	v_cvt_f32_i32_e32 v147, v45
	v_cvt_f32_i32_e32 v146, v44
	v_cvt_f32_i32_e32 v35, v35
	v_cvt_f32_i32_e32 v34, v34
	v_cvt_f32_i32_e32 v37, v37
	v_cvt_f32_i32_e32 v36, v36
	s_waitcnt vmcnt(3)
	v_mul_f32_e32 v42, v190, v178
	v_pk_mul_f32 v[72:73], v[42:43], v[72:73] op_sel_hi:[0,1]
	v_pk_mul_f32 v[70:71], v[42:43], v[70:71] op_sel_hi:[0,1]
	v_mul_f32_e32 v42, v180, v178
	v_pk_mul_f32 v[44:45], v[42:43], v[64:65] op_sel_hi:[0,1]
	v_pk_mul_f32 v[42:43], v[42:43], v[62:63] op_sel_hi:[0,1]
	s_waitcnt vmcnt(0)
	v_mul_f32_e32 v62, v190, v176
	v_pk_mul_f32 v[64:65], v[62:63], v[146:147] op_sel_hi:[0,1]
	v_pk_mul_f32 v[62:63], v[62:63], v[108:109] op_sel_hi:[0,1]
	v_mul_f32_e32 v108, v180, v176
	v_pk_mul_f32 v[36:37], v[108:109], v[36:37] op_sel_hi:[0,1]
	v_pk_mul_f32 v[34:35], v[108:109], v[34:35] op_sel_hi:[0,1]
	s_and_saveexec_b64 s[78:79], s[54:55]
	s_cbranch_execz .LBB0_1120
	v_lshl_add_u32 v107, v107, 2, v210
	ds_write_b128 v107, v[142:145]
	ds_write_b128 v107, v[138:141] offset:16
	v_mov_b64_e32 v[140:141], v[36:37]
	v_mov_b64_e32 v[144:145], v[64:65]
	v_cmp_gt_i32_e32 vcc, 15, v206
	s_mov_b64 s[80:81], -1
	v_mov_b32_e32 v107, s91
	v_mov_b64_e32 v[138:139], v[34:35]
	v_mov_b64_e32 v[142:143], v[62:63]
	s_and_saveexec_b64 s[54:55], vcc
	s_cbranch_execz .LBB0_1118
	v_cmp_eq_u32_e32 vcc, 0, v206
	s_mov_b64 s[80:81], 0
	s_and_saveexec_b64 s[82:83], vcc
	s_mov_b64 s[80:81], exec
	s_or_b64 exec, exec, s[82:83]
	v_readlane_b32 s0, v255, 11
	v_mov_b64_e32 v[140:141], v[44:45]
	v_mov_b64_e32 v[144:145], v[72:73]
	v_mov_b32_e32 v107, s0
	s_orn2_b64 s[80:81], s[80:81], exec
	v_mov_b64_e32 v[138:139], v[42:43]
	v_mov_b64_e32 v[142:143], v[70:71]
